# mixer phase: two work queues (long differential-attention tasks / short tasks); the 32 lower-numbered blocks of each XCD prefer the long queue, their CU mates the short one, each falls back to the oth
# speedup vs baseline: 1.3191x; 1.0094x over previous
.LBB0_293:
	s_andn2_b64 vcc, exec, s[0:1]
	s_cbranch_vccnz .LBB0_743
	s_lshl_b32 s0, s80, 6
	s_ashr_i32 s1, s0, 31
	s_lshl_b64 s[0:1], s[0:1], 2
	v_readlane_b32 s4, v253, 46
	s_add_u32 s14, s4, s0
	v_readlane_b32 s4, v253, 47
	s_addc_u32 s15, s4, s1
	s_lshl_b32 s28, s80, 8
	s_ashr_i32 s29, s28, 31
	s_mul_i32 s4, s80, 0x900
	s_mul_i32 s6, s80, 0x300
	s_lshl_b32 s8, s80, 7
	v_readlane_b32 s40, v252, 1
	s_ashr_i32 s5, s4, 31
	s_ashr_i32 s7, s6, 31
	s_and_b32 s38, s82, -4
	s_ashr_i32 s9, s8, 31
	s_lshl_b64 s[10:11], s[28:29], 2
	v_readlane_b32 s46, v252, 7
	v_cvt_f32_i32_e32 v0, s80
	v_readlane_b32 s47, v252, 8
	s_add_u32 s39, s46, s10
	s_mul_i32 s13, s80, 0x440000
	s_addc_u32 s11, s47, s11
	s_mul_hi_i32 s12, s80, 0x440000
	s_add_u32 s10, s78, s13
	v_writelane_b32 v255, s10, 41
	s_addc_u32 s10, s79, s12
	v_mul_f32_e32 v0, 0xbe99999a, v0
	v_writelane_b32 v255, s10, 42
	s_mov_b32 s10, s80
	v_readlane_b32 s76, v252, 45
	v_mul_f32_e32 v2, 0x3fb8aa3b, v0
	s_lshl_b64 s[4:5], s[4:5], 2
	v_readlane_b32 s78, v252, 47
	v_readlane_b32 s86, v252, 55
	v_fma_f32 v3, v0, s96, -v2
	v_rndne_f32_e32 v4, v2
	v_readlane_b32 s79, v252, 48
	v_readlane_b32 s87, v252, 56
	s_add_u32 s86, s78, s4
	v_fmac_f32_e32 v3, 0x32a5705f, v0
	v_sub_f32_e32 v2, v2, v4
	v_readlane_b32 s80, v252, 49
	v_readlane_b32 s90, v252, 59
	s_addc_u32 s87, s79, s5
	s_lshl_b64 s[4:5], s[6:7], 2
	v_add_f32_e32 v2, v2, v3
	v_readlane_b32 s81, v252, 50
	s_add_u32 s90, s80, s4
	v_readlane_b32 s52, v252, 29
	v_exp_f32_e32 v2, v2
	v_cvt_i32_f32_e32 v3, v4
	v_readlane_b32 s44, v252, 5
	s_addc_u32 s78, s81, s5
	s_lshl_b64 s[4:5], s[8:9], 2
	v_readlane_b32 s66, v252, 43
	v_readlane_b32 s45, v252, 6
	v_readlane_b32 s67, v252, 44
	s_add_u32 s44, s66, s4
	s_addc_u32 s45, s67, s5
	v_readlane_b32 s77, v252, 46
	s_add_u32 s46, s76, s0
	v_ldexp_f32 v2, v2, v3
	v_cmp_ngt_f32_e32 vcc, s68, v0
	s_addc_u32 s47, s77, s1
	s_add_u32 s0, s94, s13
	v_cndmask_b32_e32 v2, 0, v2, vcc
	v_cmp_nlt_f32_e32 vcc, s2, v0
	v_readlane_b32 s88, v252, 57
	s_addc_u32 s1, s95, s12
	v_cndmask_b32_e32 v0, v204, v2, vcc
	v_mov_b32_e32 v2, 0x3f4ccccd
	v_fmamk_f32 v154, v0, 0xbf19999a, v2
	v_readlane_b32 s82, v252, 51
	v_readlane_b32 s83, v252, 52
	v_readlane_b32 s84, v252, 53
	v_readlane_b32 s85, v252, 54
	s_add_u32 s88, s0, 0xec40000
	v_sub_f32_e32 v217, 1.0, v154
	s_mov_b32 s85, s11
	s_mov_b64 s[82:83], s[28:29]
	s_mov_b32 s79, s38
	s_mov_b32 s81, s39
	s_mov_b32 s80, s10
	s_mov_b64 s[76:77], s[14:15]
	s_addc_u32 s84, s1, 0
	v_readlane_b32 s41, v252, 2
	v_readlane_b32 s42, v252, 3
	v_readlane_b32 s43, v252, 4
	v_readlane_b32 s89, v252, 58
	v_readlane_b32 s91, v252, 60
	v_readlane_b32 s53, v252, 30
	v_readlane_b32 s54, v252, 31
	v_readlane_b32 s55, v252, 32
	v_readlane_b32 s56, v252, 33
	v_readlane_b32 s57, v252, 34
	v_readlane_b32 s58, v252, 35
	v_readlane_b32 s59, v252, 36
	v_readlane_b32 s60, v252, 37
	v_readlane_b32 s61, v252, 38
	v_readlane_b32 s62, v252, 39
	v_readlane_b32 s63, v252, 40
	v_readlane_b32 s64, v252, 41
	v_readlane_b32 s65, v252, 42
	s_mov_b32 s100, 0
	v_readlane_b32 s101, v254, 7
	s_lshr_b32 s101, s101, 5
	s_branch .LBB0_298

.Lq_retry:
	s_and_b32 s4, s100, 3
	s_cmp_eq_u32 s4, 3
	s_cbranch_scc1 .Lq_none
	s_lshr_b32 s5, s100, s101
	s_and_b32 s5, s5, 1
	s_xor_b32 s5, s5, s101
	v_mov_b32_e32 v2, 1
	s_cmp_eq_u32 s5, 0
	s_cbranch_scc0 .Lq_B
	global_atomic_add v2, v1, v2, s[76:77] sc0
	s_waitcnt vmcnt(0)
	v_readfirstlane_b32 s4, v2
	s_cmp_lt_u32 s4, 0x200
	s_cbranch_scc1 .Lq_have
	s_or_b32 s100, s100, 1
	s_branch .Lq_retry
.Lq_B:
	global_atomic_add v2, v1, v2, s[76:77] offset:128 sc0
	s_waitcnt vmcnt(0)
	v_readfirstlane_b32 s4, v2
	s_cmp_lt_u32 s4, 0x780
	s_cbranch_scc0 .Lq_Bx
	s_addk_i32 s4, 0x200
	s_branch .Lq_have
.Lq_Bx:
	s_or_b32 s100, s100, 2
	s_branch .Lq_retry
.Lq_none:
	s_movk_i32 s4, 0x980
.Lq_have:
	v_mov_b32_e32 v0, s4
	ds_write_b32 v179, v0
